# P8 sample-row conv-gate fix-up pass hand-rewritten: 4 channels per lane, 16-byte coalesced accesses, all loads issued at once
# speedup vs baseline: 1.0536x; 1.0168x over previous
.LBB0_1212:
	s_or_b64 exec, exec, s[8:9]
	s_add_u32 s10, s92, 0x15000000
	s_addc_u32 s11, s93, 0
	s_add_u32 s12, s58, 0xeefc000
	s_addc_u32 s13, s59, 0
	s_add_u32 s14, s92, 0xed00000
	s_addc_u32 s15, s93, 0
	s_lshl_b32 s17, s96, 9
	s_mov_b32 s16, 0x2c000
	s_mov_b32 s19, 0xba2e8ba3
.Lp8s_loop:
	v_cmp_gt_u32_e32 vcc, s16, v60
	s_and_saveexec_b64 s[20:21], vcc
	s_cbranch_execz .Lp8s_exit
	v_lshrrev_b32_e32 v0, 7, v60
	v_mul_hi_u32 v1, v0, s19
	v_lshrrev_b32_e32 v1, 3, v1
	v_mul_u32_u24_e32 v2, 0x580, v1
	v_sub_u32_e32 v2, v60, v2
	v_lshlrev_b32_e32 v3, 2, v2
	v_mul_u32_u24_e32 v4, 0x2c00, v1
	v_add_u32_e32 v4, v4, v3
	v_lshlrev_b32_e32 v5, 1, v4
	v_add_u32_e32 v6, 0x2c00, v5
	v_mul_u32_u24_e32 v7, 0x5800, v1
	v_add_u32_e32 v7, v7, v3
	v_lshlrev_b32_e32 v7, 2, v7
	v_add_u32_e32 v8, 0x5800, v7
	v_add_u32_e32 v9, 0xb000, v7
	v_add_u32_e32 v10, 0x10800, v7
	v_lshlrev_b32_e32 v11, 4, v2
	v_add_u32_e32 v12, 0x5800, v11
	v_add_u32_e32 v13, 0xb000, v11
	v_add_u32_e32 v14, 0x10800, v11
	v_add_u32_e32 v15, 0x16000, v11
	v_add_u32_e32 v16, 0x1b800, v11
	global_load_dwordx2 v[20:21], v5, s[10:11]
	global_load_dwordx2 v[22:23], v6, s[10:11]
	global_load_dwordx4 v[24:27], v7, s[36:37]
	global_load_dwordx4 v[28:31], v8, s[36:37]
	global_load_dwordx4 v[32:35], v9, s[36:37]
	global_load_dwordx4 v[36:39], v10, s[36:37]
	global_load_dwordx4 v[40:43], v11, s[52:53]
	global_load_dwordx4 v[44:47], v12, s[52:53]
	global_load_dwordx4 v[48:51], v13, s[52:53]
	global_load_dwordx4 v[52:55], v14, s[52:53]
	global_load_dwordx4 v[56:59], v15, s[52:53]
	global_load_dwordx4 v[64:67], v16, s[52:53]
	global_load_dwordx4 v[68:71], v11, s[54:55]
	global_load_dwordx4 v[72:75], v12, s[54:55]
	v_add_u32_e32 v17, 0x2000, v1
	v_mul_u32_u24_e32 v17, 0x1600, v17
	v_add_u32_e32 v17, v17, v3
	v_lshlrev_b32_e32 v17, 1, v17
	s_waitcnt vmcnt(0)
	v_lshlrev_b32_e32 v76, 16, v20
	v_and_b32_e32 v77, 0xffff0000, v20
	v_lshlrev_b32_e32 v78, 16, v21
	v_and_b32_e32 v79, 0xffff0000, v21
	v_lshlrev_b32_e32 v80, 16, v22
	v_and_b32_e32 v81, 0xffff0000, v22
	v_lshlrev_b32_e32 v82, 16, v23
	v_and_b32_e32 v83, 0xffff0000, v23
	global_store_dwordx4 v7, v[32:35], s[12:13]
	global_store_dwordx4 v8, v[36:39], s[12:13]
	global_store_dwordx4 v9, v[76:79], s[12:13]
	global_store_dwordx4 v10, v[80:83], s[12:13]
	v_fmac_f32_e32 v68, v40, v24
	v_fmac_f32_e32 v72, v44, v28
	v_fmac_f32_e32 v69, v41, v25
	v_fmac_f32_e32 v73, v45, v29
	v_fmac_f32_e32 v70, v42, v26
	v_fmac_f32_e32 v74, v46, v30
	v_fmac_f32_e32 v71, v43, v27
	v_fmac_f32_e32 v75, v47, v31
	v_fmac_f32_e32 v68, v48, v32
	v_fmac_f32_e32 v72, v52, v36
	v_fmac_f32_e32 v69, v49, v33
	v_fmac_f32_e32 v73, v53, v37
	v_fmac_f32_e32 v70, v50, v34
	v_fmac_f32_e32 v74, v54, v38
	v_fmac_f32_e32 v71, v51, v35
	v_fmac_f32_e32 v75, v55, v39
	v_fmac_f32_e32 v68, v56, v76
	v_fmac_f32_e32 v72, v64, v80
	v_fmac_f32_e32 v69, v57, v77
	v_fmac_f32_e32 v73, v65, v81
	v_fmac_f32_e32 v70, v58, v78
	v_fmac_f32_e32 v74, v66, v82
	v_fmac_f32_e32 v71, v59, v79
	v_fmac_f32_e32 v75, v67, v83
	v_mul_f32_e32 v84, 0xbfb8aa3b, v68
	v_mul_f32_e32 v85, 0xbfb8aa3b, v69
	v_mul_f32_e32 v86, 0xbfb8aa3b, v70
	v_mul_f32_e32 v87, 0xbfb8aa3b, v71
	v_exp_f32_e32 v84, v84
	v_exp_f32_e32 v85, v85
	v_exp_f32_e32 v86, v86
	v_exp_f32_e32 v87, v87
	s_nop 0
	v_add_f32_e32 v84, 1.0, v84
	v_add_f32_e32 v85, 1.0, v85
	v_add_f32_e32 v86, 1.0, v86
	v_add_f32_e32 v87, 1.0, v87
	v_div_scale_f32 v88, s[0:1], v84, v84, v68
	v_div_scale_f32 v89, s[0:1], v85, v85, v69
	v_div_scale_f32 v90, s[0:1], v86, v86, v70
	v_div_scale_f32 v91, s[0:1], v87, v87, v71
	v_rcp_f32_e32 v92, v88
	v_rcp_f32_e32 v93, v89
	v_rcp_f32_e32 v94, v90
	v_rcp_f32_e32 v95, v91
	s_nop 0
	v_div_scale_f32 v96, vcc, v68, v84, v68
	v_fma_f32 v97, -v88, v92, 1.0
	v_fmac_f32_e32 v92, v97, v92
	v_mul_f32_e32 v98, v96, v92
	v_fma_f32 v97, -v88, v98, v96
	v_fmac_f32_e32 v98, v97, v92
	v_fma_f32 v97, -v88, v98, v96
	v_div_fmas_f32 v97, v97, v92, v98
	v_div_fixup_f32 v100, v97, v84, v68
	v_mul_f32_e32 v100, v100, v72
	v_div_scale_f32 v96, vcc, v69, v85, v69
	v_fma_f32 v97, -v89, v93, 1.0
	v_fmac_f32_e32 v93, v97, v93
	v_mul_f32_e32 v98, v96, v93
	v_fma_f32 v97, -v89, v98, v96
	v_fmac_f32_e32 v98, v97, v93
	v_fma_f32 v97, -v89, v98, v96
	v_div_fmas_f32 v97, v97, v93, v98
	v_div_fixup_f32 v101, v97, v85, v69
	v_mul_f32_e32 v101, v101, v73
	v_div_scale_f32 v96, vcc, v70, v86, v70
	v_fma_f32 v97, -v90, v94, 1.0
	v_fmac_f32_e32 v94, v97, v94
	v_mul_f32_e32 v98, v96, v94
	v_fma_f32 v97, -v90, v98, v96
	v_fmac_f32_e32 v98, v97, v94
	v_fma_f32 v97, -v90, v98, v96
	v_div_fmas_f32 v97, v97, v94, v98
	v_div_fixup_f32 v102, v97, v86, v70
	v_mul_f32_e32 v102, v102, v74
	v_div_scale_f32 v96, vcc, v71, v87, v71
	v_fma_f32 v97, -v91, v95, 1.0
	v_fmac_f32_e32 v95, v97, v95
	v_mul_f32_e32 v98, v96, v95
	v_fma_f32 v97, -v91, v98, v96
	v_fmac_f32_e32 v98, v97, v95
	v_fma_f32 v97, -v91, v98, v96
	v_div_fmas_f32 v97, v97, v95, v98
	v_div_fixup_f32 v103, v97, v87, v71
	v_mul_f32_e32 v103, v103, v75
	v_cvt_pk_bf16_f32 v104, v100, v101
	v_cvt_pk_bf16_f32 v105, v102, v103
	global_store_dwordx2 v17, v[104:105], s[14:15]
	s_mov_b64 exec, s[20:21]
	v_add_u32_e32 v60, s17, v60
	s_branch .Lp8s_loop
.Lp8s_exit:
	s_mov_b64 exec, s[20:21]
